# S5 scan input projection moved from 16 v_pk_fma_f32 per step to exact-f32 v_mfma_f32_4x4x1_16b_f32 (same even/odd fma chains, bit-identical)
# speedup vs baseline: 1.0130x; 1.0034x over previous
; #define LAS __attribute__((address_space(3)))
; __device__ __forceinline__ unsigned f2bf(float f) { unsigned u = __builtin_bit_cast(unsigned, f); return (u + 0x7fffu + ((u >> 16) & 1u)) >> 16; }
; __device__ __forceinline__ void s5_phase(LAS unsigned char* lds, const unsigned char* ws, const bf16_t* proj, const float* c_re, const float* c_im, const float* dskip, bf16_t* z,
;                                          int vcu, int G, int wave, int lane) {
;     ...
;             if (lane < 32) {
;                 LAS f32x4* up4 = (LAS f32x4*)(Uc + lane * 16);
;                 up4[0] = (f32x4){bflo(ua.x), bfhi(ua.x), bflo(ua.y), bfhi(ua.y)}; up4[1] = (f32x4){bflo(ua.z), bfhi(ua.z), bflo(ua.w), bfhi(ua.w)};
;                 up4[2] = (f32x4){bflo(ub.x), bfhi(ub.x), bflo(ub.y), bfhi(ub.y)}; up4[3] = (f32x4){bflo(ub.z), bfhi(ub.z), bflo(ub.w), bfhi(ub.w)};
;             }
; #pragma unroll
;             for (int k = 0; k < 32; ++k) {
;                 f32x2 xa = (f32x2){0.f, 0.f}, xb = (f32x2){0.f, 0.f};
; #pragma unroll
;                 for (int q = 0; q < 4; ++q) { const f32x4 u4 = *(const LAS f32x4*)(Uc + k * 16 + 4 * q);
;                     xa = __builtin_elementwise_fma((f32x2){u4[0], u4[0]}, (f32x2){bbre[4 * q], bbim[4 * q]}, xa);
;                     xb = __builtin_elementwise_fma((f32x2){u4[1], u4[1]}, (f32x2){bbre[4 * q + 1], bbim[4 * q + 1]}, xb);
;                     xa = __builtin_elementwise_fma((f32x2){u4[2], u4[2]}, (f32x2){bbre[4 * q + 2], bbim[4 * q + 2]}, xa);
;                     xb = __builtin_elementwise_fma((f32x2){u4[3], u4[3]}, (f32x2){bbre[4 * q + 3], bbim[4 * q + 3]}, xb); }
;                 const f32x2 xx = xa + xb;
;                 const float nr = are * hre - aim * him + xx[0], ni = are * him + aim * hre + xx[1]; hre = nr; him = ni;
;                 Hc[k * 136 + n] = (bf16_t)f2bf(hre); Hc[k * 136 + 64 + n] = (bf16_t)f2bf(him);
;             }
.LBB0_386:
	s_or_b64 exec, exec, s[0:1]
	s_waitcnt vmcnt(19)
	v_mov_b32_e32 v40, s14
	v_and_b32_e32 v248, 3, v193
	v_lshl_add_u32 v248, v248, 6, v40
	s_waitcnt vmcnt(18)
	ds_read_b128 v[216:219], v248 offset:0
	ds_read_b128 v[220:223], v248 offset:16
	ds_read_b128 v[224:227], v248 offset:32
	ds_read_b128 v[228:231], v248 offset:48
	s_waitcnt lgkmcnt(0)
	v_mfma_f32_4x4x1_16b_f32 v[232:235], v216, v64, 0
	v_mfma_f32_4x4x1_16b_f32 v[236:239], v216, v65, 0
	v_mfma_f32_4x4x1_16b_f32 v[240:243], v217, v12, 0
	v_mfma_f32_4x4x1_16b_f32 v[244:247], v217, v13, 0
	v_mfma_f32_4x4x1_16b_f32 v[232:235], v218, v66, v[232:235]
	v_mfma_f32_4x4x1_16b_f32 v[236:239], v218, v67, v[236:239]
	v_mfma_f32_4x4x1_16b_f32 v[240:243], v219, v14, v[240:243]
	v_mfma_f32_4x4x1_16b_f32 v[244:247], v219, v15, v[244:247]
	v_mfma_f32_4x4x1_16b_f32 v[232:235], v220, v68, v[232:235]
	v_mfma_f32_4x4x1_16b_f32 v[236:239], v220, v69, v[236:239]
	v_mfma_f32_4x4x1_16b_f32 v[240:243], v221, v8, v[240:243]
	v_mfma_f32_4x4x1_16b_f32 v[244:247], v221, v9, v[244:247]
	v_mfma_f32_4x4x1_16b_f32 v[232:235], v222, v70, v[232:235]
	v_mfma_f32_4x4x1_16b_f32 v[236:239], v222, v71, v[236:239]
	v_mfma_f32_4x4x1_16b_f32 v[240:243], v223, v10, v[240:243]
	v_mfma_f32_4x4x1_16b_f32 v[244:247], v223, v11, v[244:247]
	v_mfma_f32_4x4x1_16b_f32 v[232:235], v224, v72, v[232:235]
	v_mfma_f32_4x4x1_16b_f32 v[236:239], v224, v73, v[236:239]
	v_mfma_f32_4x4x1_16b_f32 v[240:243], v225, v4, v[240:243]
	v_mfma_f32_4x4x1_16b_f32 v[244:247], v225, v5, v[244:247]
	v_mfma_f32_4x4x1_16b_f32 v[232:235], v226, v74, v[232:235]
	v_mfma_f32_4x4x1_16b_f32 v[236:239], v226, v75, v[236:239]
	v_mfma_f32_4x4x1_16b_f32 v[240:243], v227, v6, v[240:243]
	v_mfma_f32_4x4x1_16b_f32 v[244:247], v227, v7, v[244:247]
	v_mfma_f32_4x4x1_16b_f32 v[232:235], v228, v76, v[232:235]
	v_mfma_f32_4x4x1_16b_f32 v[236:239], v228, v77, v[236:239]
	v_mfma_f32_4x4x1_16b_f32 v[240:243], v229, v0, v[240:243]
	v_mfma_f32_4x4x1_16b_f32 v[244:247], v229, v1, v[244:247]
	v_mfma_f32_4x4x1_16b_f32 v[232:235], v230, v78, v[232:235]
	v_mfma_f32_4x4x1_16b_f32 v[236:239], v230, v79, v[236:239]
	v_mfma_f32_4x4x1_16b_f32 v[240:243], v231, v2, v[240:243]
	v_mfma_f32_4x4x1_16b_f32 v[244:247], v231, v3, v[244:247]
	s_nop 4
	s_waitcnt vmcnt(13)
	v_lshlrev_b32_e32 v108, 16, v108
	v_add_f32_e32 v42, v240, v232
	v_add_f32_e32 v43, v244, v236
	v_mul_f32_e32 v44, v61, v87
	v_pk_fma_f32 v[44:45], v[60:61], v[86:87], v[44:45] op_sel_hi:[1,1,0] neg_lo:[0,0,1] neg_hi:[0,0,1]
	s_nop 0
	v_pk_add_f32 v[46:47], v[44:45], v[42:43]
	v_mov_b32_e32 v44, v87
	v_pk_mul_f32 v[44:45], v[60:61], v[44:45]
	v_bfe_u32 v41, v46, 16, 1
	v_pk_fma_f32 v[44:45], v[50:51], v[86:87], v[44:45]
	v_add3_u32 v41, v46, v41, s29
	v_pk_add_f32 v[86:87], v[44:45], v[42:43] op_sel:[0,1] op_sel_hi:[1,0]
	ds_write_b16_d16_hi v88, v41
	v_bfe_u32 v41, v86, 16, 1
	v_add3_u32 v41, v86, v41, s29
	ds_write_b16_d16_hi v88, v41 offset:128
	v_add_f32_e32 v42, v241, v233
	v_add_f32_e32 v43, v245, v237
	v_pk_mul_f32 v[44:45], v[50:51], v[86:87]
	s_nop 0
	v_pk_fma_f32 v[44:45], v[60:61], v[46:47], v[44:45] neg_lo:[0,0,1] neg_hi:[0,0,1]
	s_nop 0
	v_pk_add_f32 v[134:135], v[44:45], v[42:43]
	v_pk_mul_f32 v[44:45], v[50:51], v[46:47]
	v_bfe_u32 v41, v134, 16, 1
	v_pk_fma_f32 v[44:45], v[60:61], v[86:87], v[44:45]
	v_add3_u32 v41, v134, v41, s29
	v_pk_add_f32 v[46:47], v[44:45], v[42:43] op_sel:[0,1] op_sel_hi:[1,0]
	ds_write_b16_d16_hi v88, v41 offset:272
	v_bfe_u32 v41, v46, 16, 1
	v_add3_u32 v41, v46, v41, s29
	ds_write_b16_d16_hi v88, v41 offset:400
	v_add_f32_e32 v42, v242, v234
	v_add_f32_e32 v43, v246, v238
	v_pk_mul_f32 v[44:45], v[50:51], v[46:47]
	s_nop 0
	v_pk_fma_f32 v[44:45], v[60:61], v[134:135], v[44:45] neg_lo:[0,0,1] neg_hi:[0,0,1]
	s_nop 0
	v_pk_add_f32 v[86:87], v[44:45], v[42:43]
	v_pk_mul_f32 v[44:45], v[50:51], v[134:135]
	v_bfe_u32 v41, v86, 16, 1
	v_pk_fma_f32 v[44:45], v[60:61], v[46:47], v[44:45]
	v_add3_u32 v41, v86, v41, s29
	v_pk_add_f32 v[46:47], v[44:45], v[42:43] op_sel:[0,1] op_sel_hi:[1,0]
	ds_write_b16_d16_hi v88, v41 offset:544
	v_bfe_u32 v41, v46, 16, 1
	v_add3_u32 v41, v46, v41, s29
	ds_write_b16_d16_hi v88, v41 offset:672
	v_add_f32_e32 v42, v243, v235
	v_add_f32_e32 v43, v247, v239
	v_pk_mul_f32 v[44:45], v[50:51], v[46:47]
	s_nop 0
	v_pk_fma_f32 v[44:45], v[60:61], v[86:87], v[44:45] neg_lo:[0,0,1] neg_hi:[0,0,1]
	s_nop 0
	v_pk_add_f32 v[134:135], v[44:45], v[42:43]
	v_pk_mul_f32 v[44:45], v[50:51], v[86:87]
	v_bfe_u32 v41, v134, 16, 1
	v_pk_fma_f32 v[44:45], v[60:61], v[46:47], v[44:45]
	v_add3_u32 v41, v134, v41, s29
	v_pk_add_f32 v[46:47], v[44:45], v[42:43] op_sel:[0,1] op_sel_hi:[1,0]
	ds_write_b16_d16_hi v88, v41 offset:816
	v_bfe_u32 v41, v46, 16, 1
	v_add3_u32 v41, v46, v41, s29
	ds_write_b16_d16_hi v88, v41 offset:944
	ds_read_b128 v[216:219], v248 offset:256
	ds_read_b128 v[220:223], v248 offset:272
	ds_read_b128 v[224:227], v248 offset:288
	ds_read_b128 v[228:231], v248 offset:304
	s_waitcnt lgkmcnt(0)
; #define LAS __attribute__((address_space(3)))
; __device__ __forceinline__ unsigned f2bf(float f) { unsigned u = __builtin_bit_cast(unsigned, f); return (u + 0x7fffu + ((u >> 16) & 1u)) >> 16; }
; __device__ __forceinline__ void s5_phase(LAS unsigned char* lds, const unsigned char* ws, const bf16_t* proj, const float* c_re, const float* c_im, const float* dskip, bf16_t* z,
;                                          int vcu, int G, int wave, int lane) {
;     ...
;             for (int k = 0; k < 32; ++k) {
;                 f32x2 xa = (f32x2){0.f, 0.f}, xb = (f32x2){0.f, 0.f};
; #pragma unroll
;                 for (int q = 0; q < 4; ++q) { const f32x4 u4 = *(const LAS f32x4*)(Uc + k * 16 + 4 * q);
;                     xa = __builtin_elementwise_fma((f32x2){u4[0], u4[0]}, (f32x2){bbre[4 * q], bbim[4 * q]}, xa);
;                     xb = __builtin_elementwise_fma((f32x2){u4[1], u4[1]}, (f32x2){bbre[4 * q + 1], bbim[4 * q + 1]}, xb);
;                     xa = __builtin_elementwise_fma((f32x2){u4[2], u4[2]}, (f32x2){bbre[4 * q + 2], bbim[4 * q + 2]}, xa);
;                     xb = __builtin_elementwise_fma((f32x2){u4[3], u4[3]}, (f32x2){bbre[4 * q + 3], bbim[4 * q + 3]}, xb); }
;                 const f32x2 xx = xa + xb;
;                 const float nr = are * hre - aim * him + xx[0], ni = are * him + aim * hre + xx[1]; hre = nr; him = ni;
;                 Hc[k * 136 + n] = (bf16_t)f2bf(hre); Hc[k * 136 + 64 + n] = (bf16_t)f2bf(him);
;             }
	v_mfma_f32_4x4x1_16b_f32 v[232:235], v216, v64, 0
	v_mfma_f32_4x4x1_16b_f32 v[236:239], v216, v65, 0
	v_mfma_f32_4x4x1_16b_f32 v[240:243], v217, v12, 0
	v_mfma_f32_4x4x1_16b_f32 v[244:247], v217, v13, 0
	v_mfma_f32_4x4x1_16b_f32 v[232:235], v218, v66, v[232:235]
	v_mfma_f32_4x4x1_16b_f32 v[236:239], v218, v67, v[236:239]
	v_mfma_f32_4x4x1_16b_f32 v[240:243], v219, v14, v[240:243]
	v_mfma_f32_4x4x1_16b_f32 v[244:247], v219, v15, v[244:247]
	v_mfma_f32_4x4x1_16b_f32 v[232:235], v220, v68, v[232:235]
	v_mfma_f32_4x4x1_16b_f32 v[236:239], v220, v69, v[236:239]
	v_mfma_f32_4x4x1_16b_f32 v[240:243], v221, v8, v[240:243]
	v_mfma_f32_4x4x1_16b_f32 v[244:247], v221, v9, v[244:247]
	v_mfma_f32_4x4x1_16b_f32 v[232:235], v222, v70, v[232:235]
	v_mfma_f32_4x4x1_16b_f32 v[236:239], v222, v71, v[236:239]
	v_mfma_f32_4x4x1_16b_f32 v[240:243], v223, v10, v[240:243]
	v_mfma_f32_4x4x1_16b_f32 v[244:247], v223, v11, v[244:247]
	v_mfma_f32_4x4x1_16b_f32 v[232:235], v224, v72, v[232:235]
	v_mfma_f32_4x4x1_16b_f32 v[236:239], v224, v73, v[236:239]
	v_mfma_f32_4x4x1_16b_f32 v[240:243], v225, v4, v[240:243]
	v_mfma_f32_4x4x1_16b_f32 v[244:247], v225, v5, v[244:247]
	v_mfma_f32_4x4x1_16b_f32 v[232:235], v226, v74, v[232:235]
	v_mfma_f32_4x4x1_16b_f32 v[236:239], v226, v75, v[236:239]
	v_mfma_f32_4x4x1_16b_f32 v[240:243], v227, v6, v[240:243]
	v_mfma_f32_4x4x1_16b_f32 v[244:247], v227, v7, v[244:247]
	v_mfma_f32_4x4x1_16b_f32 v[232:235], v228, v76, v[232:235]
	v_mfma_f32_4x4x1_16b_f32 v[236:239], v228, v77, v[236:239]
	v_mfma_f32_4x4x1_16b_f32 v[240:243], v229, v0, v[240:243]
	v_mfma_f32_4x4x1_16b_f32 v[244:247], v229, v1, v[244:247]
	v_mfma_f32_4x4x1_16b_f32 v[232:235], v230, v78, v[232:235]
	v_mfma_f32_4x4x1_16b_f32 v[236:239], v230, v79, v[236:239]
	v_mfma_f32_4x4x1_16b_f32 v[240:243], v231, v2, v[240:243]
	v_mfma_f32_4x4x1_16b_f32 v[244:247], v231, v3, v[244:247]
	s_nop 4
	v_add_f32_e32 v42, v240, v232
	v_add_f32_e32 v43, v244, v236
	v_pk_mul_f32 v[44:45], v[50:51], v[46:47]
	s_nop 0
	v_pk_fma_f32 v[44:45], v[60:61], v[134:135], v[44:45] neg_lo:[0,0,1] neg_hi:[0,0,1]
	s_nop 0
	v_pk_add_f32 v[86:87], v[44:45], v[42:43]
	v_pk_mul_f32 v[44:45], v[50:51], v[134:135]
	v_bfe_u32 v41, v86, 16, 1
	v_pk_fma_f32 v[44:45], v[60:61], v[46:47], v[44:45]
	v_add3_u32 v41, v86, v41, s29
	v_pk_add_f32 v[46:47], v[44:45], v[42:43] op_sel:[0,1] op_sel_hi:[1,0]
	ds_write_b16_d16_hi v88, v41 offset:1088
	v_bfe_u32 v41, v46, 16, 1
	v_add3_u32 v41, v46, v41, s29
	ds_write_b16_d16_hi v88, v41 offset:1216
	v_add_f32_e32 v42, v241, v233
	v_add_f32_e32 v43, v245, v237
	v_pk_mul_f32 v[44:45], v[50:51], v[46:47]
	s_nop 0
	v_pk_fma_f32 v[44:45], v[60:61], v[86:87], v[44:45] neg_lo:[0,0,1] neg_hi:[0,0,1]
	s_nop 0
	v_pk_add_f32 v[134:135], v[44:45], v[42:43]
	v_pk_mul_f32 v[44:45], v[50:51], v[86:87]
	v_bfe_u32 v41, v134, 16, 1
	v_pk_fma_f32 v[44:45], v[60:61], v[46:47], v[44:45]
	v_add3_u32 v41, v134, v41, s29
	v_pk_add_f32 v[46:47], v[44:45], v[42:43] op_sel:[0,1] op_sel_hi:[1,0]
	ds_write_b16_d16_hi v88, v41 offset:1360
	v_bfe_u32 v41, v46, 16, 1
	v_add3_u32 v41, v46, v41, s29
	ds_write_b16_d16_hi v88, v41 offset:1488
	v_add_f32_e32 v42, v242, v234
	v_add_f32_e32 v43, v246, v238
	v_pk_mul_f32 v[44:45], v[50:51], v[46:47]
	s_nop 0
	v_pk_fma_f32 v[44:45], v[60:61], v[134:135], v[44:45] neg_lo:[0,0,1] neg_hi:[0,0,1]
	s_nop 0
	v_pk_add_f32 v[86:87], v[44:45], v[42:43]
	v_pk_mul_f32 v[44:45], v[50:51], v[134:135]
	v_bfe_u32 v41, v86, 16, 1
	v_pk_fma_f32 v[44:45], v[60:61], v[46:47], v[44:45]
	v_add3_u32 v41, v86, v41, s29
	v_pk_add_f32 v[46:47], v[44:45], v[42:43] op_sel:[0,1] op_sel_hi:[1,0]
	ds_write_b16_d16_hi v88, v41 offset:1632
	v_bfe_u32 v41, v46, 16, 1
	v_add3_u32 v41, v46, v41, s29
	ds_write_b16_d16_hi v88, v41 offset:1760
	v_add_f32_e32 v42, v243, v235
	v_add_f32_e32 v43, v247, v239
	v_pk_mul_f32 v[44:45], v[50:51], v[46:47]
	s_nop 0
	v_pk_fma_f32 v[44:45], v[60:61], v[86:87], v[44:45] neg_lo:[0,0,1] neg_hi:[0,0,1]
	s_nop 0
	v_pk_add_f32 v[134:135], v[44:45], v[42:43]
	v_pk_mul_f32 v[44:45], v[50:51], v[86:87]
	v_bfe_u32 v41, v134, 16, 1
	v_pk_fma_f32 v[44:45], v[60:61], v[46:47], v[44:45]
	v_add3_u32 v41, v134, v41, s29
	v_pk_add_f32 v[46:47], v[44:45], v[42:43] op_sel:[0,1] op_sel_hi:[1,0]
	ds_write_b16_d16_hi v88, v41 offset:1904
	v_bfe_u32 v41, v46, 16, 1
	v_add3_u32 v41, v46, v41, s29
	ds_write_b16_d16_hi v88, v41 offset:2032
	ds_read_b128 v[216:219], v248 offset:512
	ds_read_b128 v[220:223], v248 offset:528
	ds_read_b128 v[224:227], v248 offset:544
	ds_read_b128 v[228:231], v248 offset:560
	s_waitcnt lgkmcnt(0)
; #define LAS __attribute__((address_space(3)))
; __device__ __forceinline__ unsigned f2bf(float f) { unsigned u = __builtin_bit_cast(unsigned, f); return (u + 0x7fffu + ((u >> 16) & 1u)) >> 16; }
; __device__ __forceinline__ void s5_phase(LAS unsigned char* lds, const unsigned char* ws, const bf16_t* proj, const float* c_re, const float* c_im, const float* dskip, bf16_t* z,
;                                          int vcu, int G, int wave, int lane) {
;     ...
;             for (int k = 0; k < 32; ++k) {
;                 f32x2 xa = (f32x2){0.f, 0.f}, xb = (f32x2){0.f, 0.f};
; #pragma unroll
;                 for (int q = 0; q < 4; ++q) { const f32x4 u4 = *(const LAS f32x4*)(Uc + k * 16 + 4 * q);
;                     xa = __builtin_elementwise_fma((f32x2){u4[0], u4[0]}, (f32x2){bbre[4 * q], bbim[4 * q]}, xa);
;                     xb = __builtin_elementwise_fma((f32x2){u4[1], u4[1]}, (f32x2){bbre[4 * q + 1], bbim[4 * q + 1]}, xb);
;                     xa = __builtin_elementwise_fma((f32x2){u4[2], u4[2]}, (f32x2){bbre[4 * q + 2], bbim[4 * q + 2]}, xa);
;                     xb = __builtin_elementwise_fma((f32x2){u4[3], u4[3]}, (f32x2){bbre[4 * q + 3], bbim[4 * q + 3]}, xb); }
;                 const f32x2 xx = xa + xb;
;                 const float nr = are * hre - aim * him + xx[0], ni = are * him + aim * hre + xx[1]; hre = nr; him = ni;
;                 Hc[k * 136 + n] = (bf16_t)f2bf(hre); Hc[k * 136 + 64 + n] = (bf16_t)f2bf(him);
;             }
	v_mfma_f32_4x4x1_16b_f32 v[232:235], v216, v64, 0
	v_mfma_f32_4x4x1_16b_f32 v[236:239], v216, v65, 0
	v_mfma_f32_4x4x1_16b_f32 v[240:243], v217, v12, 0
	v_mfma_f32_4x4x1_16b_f32 v[244:247], v217, v13, 0
	v_mfma_f32_4x4x1_16b_f32 v[232:235], v218, v66, v[232:235]
	v_mfma_f32_4x4x1_16b_f32 v[236:239], v218, v67, v[236:239]
	v_mfma_f32_4x4x1_16b_f32 v[240:243], v219, v14, v[240:243]
	v_mfma_f32_4x4x1_16b_f32 v[244:247], v219, v15, v[244:247]
	v_mfma_f32_4x4x1_16b_f32 v[232:235], v220, v68, v[232:235]
	v_mfma_f32_4x4x1_16b_f32 v[236:239], v220, v69, v[236:239]
	v_mfma_f32_4x4x1_16b_f32 v[240:243], v221, v8, v[240:243]
	v_mfma_f32_4x4x1_16b_f32 v[244:247], v221, v9, v[244:247]
	v_mfma_f32_4x4x1_16b_f32 v[232:235], v222, v70, v[232:235]
	v_mfma_f32_4x4x1_16b_f32 v[236:239], v222, v71, v[236:239]
	v_mfma_f32_4x4x1_16b_f32 v[240:243], v223, v10, v[240:243]
	v_mfma_f32_4x4x1_16b_f32 v[244:247], v223, v11, v[244:247]
	v_mfma_f32_4x4x1_16b_f32 v[232:235], v224, v72, v[232:235]
	v_mfma_f32_4x4x1_16b_f32 v[236:239], v224, v73, v[236:239]
	v_mfma_f32_4x4x1_16b_f32 v[240:243], v225, v4, v[240:243]
	v_mfma_f32_4x4x1_16b_f32 v[244:247], v225, v5, v[244:247]
	v_mfma_f32_4x4x1_16b_f32 v[232:235], v226, v74, v[232:235]
	v_mfma_f32_4x4x1_16b_f32 v[236:239], v226, v75, v[236:239]
	v_mfma_f32_4x4x1_16b_f32 v[240:243], v227, v6, v[240:243]
	v_mfma_f32_4x4x1_16b_f32 v[244:247], v227, v7, v[244:247]
	v_mfma_f32_4x4x1_16b_f32 v[232:235], v228, v76, v[232:235]
	v_mfma_f32_4x4x1_16b_f32 v[236:239], v228, v77, v[236:239]
	v_mfma_f32_4x4x1_16b_f32 v[240:243], v229, v0, v[240:243]
	v_mfma_f32_4x4x1_16b_f32 v[244:247], v229, v1, v[244:247]
	v_mfma_f32_4x4x1_16b_f32 v[232:235], v230, v78, v[232:235]
	v_mfma_f32_4x4x1_16b_f32 v[236:239], v230, v79, v[236:239]
	v_mfma_f32_4x4x1_16b_f32 v[240:243], v231, v2, v[240:243]
	v_mfma_f32_4x4x1_16b_f32 v[244:247], v231, v3, v[244:247]
	s_nop 4
	v_add_f32_e32 v42, v240, v232
	v_add_f32_e32 v43, v244, v236
	v_pk_mul_f32 v[44:45], v[50:51], v[46:47]
	s_nop 0
	v_pk_fma_f32 v[44:45], v[60:61], v[134:135], v[44:45] neg_lo:[0,0,1] neg_hi:[0,0,1]
	s_nop 0
	v_pk_add_f32 v[86:87], v[44:45], v[42:43]
	v_pk_mul_f32 v[44:45], v[50:51], v[134:135]
	v_bfe_u32 v41, v86, 16, 1
	v_pk_fma_f32 v[44:45], v[60:61], v[46:47], v[44:45]
	v_add3_u32 v41, v86, v41, s29
	v_pk_add_f32 v[46:47], v[44:45], v[42:43] op_sel:[0,1] op_sel_hi:[1,0]
	ds_write_b16_d16_hi v88, v41 offset:2176
	v_bfe_u32 v41, v46, 16, 1
	v_add3_u32 v41, v46, v41, s29
	ds_write_b16_d16_hi v88, v41 offset:2304
	v_add_f32_e32 v42, v241, v233
	v_add_f32_e32 v43, v245, v237
	v_pk_mul_f32 v[44:45], v[50:51], v[46:47]
	s_nop 0
	v_pk_fma_f32 v[44:45], v[60:61], v[86:87], v[44:45] neg_lo:[0,0,1] neg_hi:[0,0,1]
	s_nop 0
	v_pk_add_f32 v[134:135], v[44:45], v[42:43]
	v_pk_mul_f32 v[44:45], v[50:51], v[86:87]
	v_bfe_u32 v41, v134, 16, 1
	v_pk_fma_f32 v[44:45], v[60:61], v[46:47], v[44:45]
	v_add3_u32 v41, v134, v41, s29
	v_pk_add_f32 v[46:47], v[44:45], v[42:43] op_sel:[0,1] op_sel_hi:[1,0]
	ds_write_b16_d16_hi v88, v41 offset:2448
	v_bfe_u32 v41, v46, 16, 1
	v_add3_u32 v41, v46, v41, s29
	ds_write_b16_d16_hi v88, v41 offset:2576
	v_add_f32_e32 v42, v242, v234
	v_add_f32_e32 v43, v246, v238
	v_pk_mul_f32 v[44:45], v[50:51], v[46:47]
	s_nop 0
	v_pk_fma_f32 v[44:45], v[60:61], v[134:135], v[44:45] neg_lo:[0,0,1] neg_hi:[0,0,1]
	s_nop 0
	v_pk_add_f32 v[86:87], v[44:45], v[42:43]
	v_pk_mul_f32 v[44:45], v[50:51], v[134:135]
	v_bfe_u32 v41, v86, 16, 1
	v_pk_fma_f32 v[44:45], v[60:61], v[46:47], v[44:45]
	v_add3_u32 v41, v86, v41, s29
	v_pk_add_f32 v[46:47], v[44:45], v[42:43] op_sel:[0,1] op_sel_hi:[1,0]
	ds_write_b16_d16_hi v88, v41 offset:2720
	v_bfe_u32 v41, v46, 16, 1
	v_add3_u32 v41, v46, v41, s29
	ds_write_b16_d16_hi v88, v41 offset:2848
	v_add_f32_e32 v42, v243, v235
	v_add_f32_e32 v43, v247, v239
	v_pk_mul_f32 v[44:45], v[50:51], v[46:47]
	s_nop 0
	v_pk_fma_f32 v[44:45], v[60:61], v[86:87], v[44:45] neg_lo:[0,0,1] neg_hi:[0,0,1]
	s_nop 0
	v_pk_add_f32 v[134:135], v[44:45], v[42:43]
	v_pk_mul_f32 v[44:45], v[50:51], v[86:87]
	v_bfe_u32 v41, v134, 16, 1
	v_pk_fma_f32 v[44:45], v[60:61], v[46:47], v[44:45]
	v_add3_u32 v41, v134, v41, s29
	v_pk_add_f32 v[46:47], v[44:45], v[42:43] op_sel:[0,1] op_sel_hi:[1,0]
	ds_write_b16_d16_hi v88, v41 offset:2992
	v_bfe_u32 v41, v46, 16, 1
	v_add3_u32 v41, v46, v41, s29
	ds_write_b16_d16_hi v88, v41 offset:3120
	ds_read_b128 v[216:219], v248 offset:768
	ds_read_b128 v[220:223], v248 offset:784
	ds_read_b128 v[224:227], v248 offset:800
	ds_read_b128 v[228:231], v248 offset:816
	s_waitcnt lgkmcnt(0)
; #define LAS __attribute__((address_space(3)))
; __device__ __forceinline__ unsigned f2bf(float f) { unsigned u = __builtin_bit_cast(unsigned, f); return (u + 0x7fffu + ((u >> 16) & 1u)) >> 16; }
; __device__ __forceinline__ void s5_phase(LAS unsigned char* lds, const unsigned char* ws, const bf16_t* proj, const float* c_re, const float* c_im, const float* dskip, bf16_t* z,
;                                          int vcu, int G, int wave, int lane) {
;     ...
;             for (int k = 0; k < 32; ++k) {
;                 f32x2 xa = (f32x2){0.f, 0.f}, xb = (f32x2){0.f, 0.f};
; #pragma unroll
;                 for (int q = 0; q < 4; ++q) { const f32x4 u4 = *(const LAS f32x4*)(Uc + k * 16 + 4 * q);
;                     xa = __builtin_elementwise_fma((f32x2){u4[0], u4[0]}, (f32x2){bbre[4 * q], bbim[4 * q]}, xa);
;                     xb = __builtin_elementwise_fma((f32x2){u4[1], u4[1]}, (f32x2){bbre[4 * q + 1], bbim[4 * q + 1]}, xb);
;                     xa = __builtin_elementwise_fma((f32x2){u4[2], u4[2]}, (f32x2){bbre[4 * q + 2], bbim[4 * q + 2]}, xa);
;                     xb = __builtin_elementwise_fma((f32x2){u4[3], u4[3]}, (f32x2){bbre[4 * q + 3], bbim[4 * q + 3]}, xb); }
;                 const f32x2 xx = xa + xb;
;                 const float nr = are * hre - aim * him + xx[0], ni = are * him + aim * hre + xx[1]; hre = nr; him = ni;
;                 Hc[k * 136 + n] = (bf16_t)f2bf(hre); Hc[k * 136 + 64 + n] = (bf16_t)f2bf(him);
;             }
	v_mfma_f32_4x4x1_16b_f32 v[232:235], v216, v64, 0
	v_mfma_f32_4x4x1_16b_f32 v[236:239], v216, v65, 0
	v_mfma_f32_4x4x1_16b_f32 v[240:243], v217, v12, 0
	v_mfma_f32_4x4x1_16b_f32 v[244:247], v217, v13, 0
	v_mfma_f32_4x4x1_16b_f32 v[232:235], v218, v66, v[232:235]
	v_mfma_f32_4x4x1_16b_f32 v[236:239], v218, v67, v[236:239]
	v_mfma_f32_4x4x1_16b_f32 v[240:243], v219, v14, v[240:243]
	v_mfma_f32_4x4x1_16b_f32 v[244:247], v219, v15, v[244:247]
	v_mfma_f32_4x4x1_16b_f32 v[232:235], v220, v68, v[232:235]
	v_mfma_f32_4x4x1_16b_f32 v[236:239], v220, v69, v[236:239]
	v_mfma_f32_4x4x1_16b_f32 v[240:243], v221, v8, v[240:243]
	v_mfma_f32_4x4x1_16b_f32 v[244:247], v221, v9, v[244:247]
	v_mfma_f32_4x4x1_16b_f32 v[232:235], v222, v70, v[232:235]
	v_mfma_f32_4x4x1_16b_f32 v[236:239], v222, v71, v[236:239]
	v_mfma_f32_4x4x1_16b_f32 v[240:243], v223, v10, v[240:243]
	v_mfma_f32_4x4x1_16b_f32 v[244:247], v223, v11, v[244:247]
	v_mfma_f32_4x4x1_16b_f32 v[232:235], v224, v72, v[232:235]
	v_mfma_f32_4x4x1_16b_f32 v[236:239], v224, v73, v[236:239]
	v_mfma_f32_4x4x1_16b_f32 v[240:243], v225, v4, v[240:243]
	v_mfma_f32_4x4x1_16b_f32 v[244:247], v225, v5, v[244:247]
	v_mfma_f32_4x4x1_16b_f32 v[232:235], v226, v74, v[232:235]
	v_mfma_f32_4x4x1_16b_f32 v[236:239], v226, v75, v[236:239]
	v_mfma_f32_4x4x1_16b_f32 v[240:243], v227, v6, v[240:243]
	v_mfma_f32_4x4x1_16b_f32 v[244:247], v227, v7, v[244:247]
	v_mfma_f32_4x4x1_16b_f32 v[232:235], v228, v76, v[232:235]
	v_mfma_f32_4x4x1_16b_f32 v[236:239], v228, v77, v[236:239]
	v_mfma_f32_4x4x1_16b_f32 v[240:243], v229, v0, v[240:243]
	v_mfma_f32_4x4x1_16b_f32 v[244:247], v229, v1, v[244:247]
	v_mfma_f32_4x4x1_16b_f32 v[232:235], v230, v78, v[232:235]
	v_mfma_f32_4x4x1_16b_f32 v[236:239], v230, v79, v[236:239]
	v_mfma_f32_4x4x1_16b_f32 v[240:243], v231, v2, v[240:243]
	v_mfma_f32_4x4x1_16b_f32 v[244:247], v231, v3, v[244:247]
	s_nop 4
	v_add_f32_e32 v42, v240, v232
	v_add_f32_e32 v43, v244, v236
	v_pk_mul_f32 v[44:45], v[50:51], v[46:47]
	s_nop 0
	v_pk_fma_f32 v[44:45], v[60:61], v[134:135], v[44:45] neg_lo:[0,0,1] neg_hi:[0,0,1]
	s_nop 0
	v_pk_add_f32 v[86:87], v[44:45], v[42:43]
	v_pk_mul_f32 v[44:45], v[50:51], v[134:135]
	v_bfe_u32 v41, v86, 16, 1
	v_pk_fma_f32 v[44:45], v[60:61], v[46:47], v[44:45]
	v_add3_u32 v41, v86, v41, s29
	v_pk_add_f32 v[46:47], v[44:45], v[42:43] op_sel:[0,1] op_sel_hi:[1,0]
	ds_write_b16_d16_hi v88, v41 offset:3264
	v_bfe_u32 v41, v46, 16, 1
	v_add3_u32 v41, v46, v41, s29
	ds_write_b16_d16_hi v88, v41 offset:3392
	v_add_f32_e32 v42, v241, v233
	v_add_f32_e32 v43, v245, v237
	v_pk_mul_f32 v[44:45], v[50:51], v[46:47]
	s_nop 0
	v_pk_fma_f32 v[44:45], v[60:61], v[86:87], v[44:45] neg_lo:[0,0,1] neg_hi:[0,0,1]
	s_nop 0
	v_pk_add_f32 v[134:135], v[44:45], v[42:43]
	v_pk_mul_f32 v[44:45], v[50:51], v[86:87]
	v_bfe_u32 v41, v134, 16, 1
	v_pk_fma_f32 v[44:45], v[60:61], v[46:47], v[44:45]
	v_add3_u32 v41, v134, v41, s29
	v_pk_add_f32 v[46:47], v[44:45], v[42:43] op_sel:[0,1] op_sel_hi:[1,0]
	ds_write_b16_d16_hi v88, v41 offset:3536
	v_bfe_u32 v41, v46, 16, 1
	v_add3_u32 v41, v46, v41, s29
	ds_write_b16_d16_hi v88, v41 offset:3664
	v_add_f32_e32 v42, v242, v234
	v_add_f32_e32 v43, v246, v238
	v_pk_mul_f32 v[44:45], v[50:51], v[46:47]
	s_nop 0
	v_pk_fma_f32 v[44:45], v[60:61], v[134:135], v[44:45] neg_lo:[0,0,1] neg_hi:[0,0,1]
	s_nop 0
	v_pk_add_f32 v[86:87], v[44:45], v[42:43]
	v_pk_mul_f32 v[44:45], v[50:51], v[134:135]
	v_bfe_u32 v41, v86, 16, 1
	v_pk_fma_f32 v[44:45], v[60:61], v[46:47], v[44:45]
	v_add3_u32 v41, v86, v41, s29
	v_pk_add_f32 v[46:47], v[44:45], v[42:43] op_sel:[0,1] op_sel_hi:[1,0]
	ds_write_b16_d16_hi v88, v41 offset:3808
	v_bfe_u32 v41, v46, 16, 1
	v_add3_u32 v41, v46, v41, s29
	ds_write_b16_d16_hi v88, v41 offset:3936
	v_add_f32_e32 v42, v243, v235
	v_add_f32_e32 v43, v247, v239
	v_pk_mul_f32 v[44:45], v[50:51], v[46:47]
	s_nop 0
	v_pk_fma_f32 v[44:45], v[60:61], v[86:87], v[44:45] neg_lo:[0,0,1] neg_hi:[0,0,1]
	s_nop 0
	v_pk_add_f32 v[134:135], v[44:45], v[42:43]
	v_pk_mul_f32 v[44:45], v[50:51], v[86:87]
	v_bfe_u32 v41, v134, 16, 1
	v_pk_fma_f32 v[44:45], v[60:61], v[46:47], v[44:45]
	v_add3_u32 v41, v134, v41, s29
	v_pk_add_f32 v[46:47], v[44:45], v[42:43] op_sel:[0,1] op_sel_hi:[1,0]
	ds_write_b16_d16_hi v88, v41 offset:4080
	v_bfe_u32 v41, v46, 16, 1
	v_add3_u32 v41, v46, v41, s29
	ds_write_b16_d16_hi v88, v41 offset:4208
	ds_read_b128 v[216:219], v248 offset:1024
	ds_read_b128 v[220:223], v248 offset:1040
	ds_read_b128 v[224:227], v248 offset:1056
	ds_read_b128 v[228:231], v248 offset:1072
	s_waitcnt lgkmcnt(0)
; #define LAS __attribute__((address_space(3)))
; __device__ __forceinline__ unsigned f2bf(float f) { unsigned u = __builtin_bit_cast(unsigned, f); return (u + 0x7fffu + ((u >> 16) & 1u)) >> 16; }
; __device__ __forceinline__ void s5_phase(LAS unsigned char* lds, const unsigned char* ws, const bf16_t* proj, const float* c_re, const float* c_im, const float* dskip, bf16_t* z,
;                                          int vcu, int G, int wave, int lane) {
;     ...
;             for (int k = 0; k < 32; ++k) {
;                 f32x2 xa = (f32x2){0.f, 0.f}, xb = (f32x2){0.f, 0.f};
; #pragma unroll
;                 for (int q = 0; q < 4; ++q) { const f32x4 u4 = *(const LAS f32x4*)(Uc + k * 16 + 4 * q);
;                     xa = __builtin_elementwise_fma((f32x2){u4[0], u4[0]}, (f32x2){bbre[4 * q], bbim[4 * q]}, xa);
;                     xb = __builtin_elementwise_fma((f32x2){u4[1], u4[1]}, (f32x2){bbre[4 * q + 1], bbim[4 * q + 1]}, xb);
;                     xa = __builtin_elementwise_fma((f32x2){u4[2], u4[2]}, (f32x2){bbre[4 * q + 2], bbim[4 * q + 2]}, xa);
;                     xb = __builtin_elementwise_fma((f32x2){u4[3], u4[3]}, (f32x2){bbre[4 * q + 3], bbim[4 * q + 3]}, xb); }
;                 const f32x2 xx = xa + xb;
;                 const float nr = are * hre - aim * him + xx[0], ni = are * him + aim * hre + xx[1]; hre = nr; him = ni;
;                 Hc[k * 136 + n] = (bf16_t)f2bf(hre); Hc[k * 136 + 64 + n] = (bf16_t)f2bf(him);
;             }
	v_mfma_f32_4x4x1_16b_f32 v[232:235], v216, v64, 0
	v_mfma_f32_4x4x1_16b_f32 v[236:239], v216, v65, 0
	v_mfma_f32_4x4x1_16b_f32 v[240:243], v217, v12, 0
	v_mfma_f32_4x4x1_16b_f32 v[244:247], v217, v13, 0
	v_mfma_f32_4x4x1_16b_f32 v[232:235], v218, v66, v[232:235]
	v_mfma_f32_4x4x1_16b_f32 v[236:239], v218, v67, v[236:239]
	v_mfma_f32_4x4x1_16b_f32 v[240:243], v219, v14, v[240:243]
	v_mfma_f32_4x4x1_16b_f32 v[244:247], v219, v15, v[244:247]
	v_mfma_f32_4x4x1_16b_f32 v[232:235], v220, v68, v[232:235]
	v_mfma_f32_4x4x1_16b_f32 v[236:239], v220, v69, v[236:239]
	v_mfma_f32_4x4x1_16b_f32 v[240:243], v221, v8, v[240:243]
	v_mfma_f32_4x4x1_16b_f32 v[244:247], v221, v9, v[244:247]
	v_mfma_f32_4x4x1_16b_f32 v[232:235], v222, v70, v[232:235]
	v_mfma_f32_4x4x1_16b_f32 v[236:239], v222, v71, v[236:239]
	v_mfma_f32_4x4x1_16b_f32 v[240:243], v223, v10, v[240:243]
	v_mfma_f32_4x4x1_16b_f32 v[244:247], v223, v11, v[244:247]
	v_mfma_f32_4x4x1_16b_f32 v[232:235], v224, v72, v[232:235]
	v_mfma_f32_4x4x1_16b_f32 v[236:239], v224, v73, v[236:239]
	v_mfma_f32_4x4x1_16b_f32 v[240:243], v225, v4, v[240:243]
	v_mfma_f32_4x4x1_16b_f32 v[244:247], v225, v5, v[244:247]
	v_mfma_f32_4x4x1_16b_f32 v[232:235], v226, v74, v[232:235]
	v_mfma_f32_4x4x1_16b_f32 v[236:239], v226, v75, v[236:239]
	v_mfma_f32_4x4x1_16b_f32 v[240:243], v227, v6, v[240:243]
	v_mfma_f32_4x4x1_16b_f32 v[244:247], v227, v7, v[244:247]
	v_mfma_f32_4x4x1_16b_f32 v[232:235], v228, v76, v[232:235]
	v_mfma_f32_4x4x1_16b_f32 v[236:239], v228, v77, v[236:239]
	v_mfma_f32_4x4x1_16b_f32 v[240:243], v229, v0, v[240:243]
	v_mfma_f32_4x4x1_16b_f32 v[244:247], v229, v1, v[244:247]
	v_mfma_f32_4x4x1_16b_f32 v[232:235], v230, v78, v[232:235]
	v_mfma_f32_4x4x1_16b_f32 v[236:239], v230, v79, v[236:239]
	v_mfma_f32_4x4x1_16b_f32 v[240:243], v231, v2, v[240:243]
	v_mfma_f32_4x4x1_16b_f32 v[244:247], v231, v3, v[244:247]
	s_nop 4
	v_add_f32_e32 v42, v240, v232
	v_add_f32_e32 v43, v244, v236
	v_pk_mul_f32 v[44:45], v[50:51], v[46:47]
	s_nop 0
	v_pk_fma_f32 v[44:45], v[60:61], v[134:135], v[44:45] neg_lo:[0,0,1] neg_hi:[0,0,1]
	s_nop 0
	v_pk_add_f32 v[86:87], v[44:45], v[42:43]
	v_pk_mul_f32 v[44:45], v[50:51], v[134:135]
	v_bfe_u32 v41, v86, 16, 1
	v_pk_fma_f32 v[44:45], v[60:61], v[46:47], v[44:45]
	v_add3_u32 v41, v86, v41, s29
	v_pk_add_f32 v[46:47], v[44:45], v[42:43] op_sel:[0,1] op_sel_hi:[1,0]
	ds_write_b16_d16_hi v88, v41 offset:4352
	v_bfe_u32 v41, v46, 16, 1
	v_add3_u32 v41, v46, v41, s29
	ds_write_b16_d16_hi v88, v41 offset:4480
	v_add_f32_e32 v42, v241, v233
	v_add_f32_e32 v43, v245, v237
	v_pk_mul_f32 v[44:45], v[50:51], v[46:47]
	s_nop 0
	v_pk_fma_f32 v[44:45], v[60:61], v[86:87], v[44:45] neg_lo:[0,0,1] neg_hi:[0,0,1]
	s_nop 0
	v_pk_add_f32 v[134:135], v[44:45], v[42:43]
	v_pk_mul_f32 v[44:45], v[50:51], v[86:87]
	v_bfe_u32 v41, v134, 16, 1
	v_pk_fma_f32 v[44:45], v[60:61], v[46:47], v[44:45]
	v_add3_u32 v41, v134, v41, s29
	v_pk_add_f32 v[46:47], v[44:45], v[42:43] op_sel:[0,1] op_sel_hi:[1,0]
	ds_write_b16_d16_hi v88, v41 offset:4624
	v_bfe_u32 v41, v46, 16, 1
	v_add3_u32 v41, v46, v41, s29
	ds_write_b16_d16_hi v88, v41 offset:4752
	v_add_f32_e32 v42, v242, v234
	v_add_f32_e32 v43, v246, v238
	v_pk_mul_f32 v[44:45], v[50:51], v[46:47]
	s_nop 0
	v_pk_fma_f32 v[44:45], v[60:61], v[134:135], v[44:45] neg_lo:[0,0,1] neg_hi:[0,0,1]
	s_nop 0
	v_pk_add_f32 v[86:87], v[44:45], v[42:43]
	v_pk_mul_f32 v[44:45], v[50:51], v[134:135]
	v_bfe_u32 v41, v86, 16, 1
	v_pk_fma_f32 v[44:45], v[60:61], v[46:47], v[44:45]
	v_add3_u32 v41, v86, v41, s29
	v_pk_add_f32 v[46:47], v[44:45], v[42:43] op_sel:[0,1] op_sel_hi:[1,0]
	ds_write_b16_d16_hi v88, v41 offset:4896
	v_bfe_u32 v41, v46, 16, 1
	v_add3_u32 v41, v46, v41, s29
	ds_write_b16_d16_hi v88, v41 offset:5024
	v_add_f32_e32 v42, v243, v235
	v_add_f32_e32 v43, v247, v239
	v_pk_mul_f32 v[44:45], v[50:51], v[46:47]
	s_nop 0
	v_pk_fma_f32 v[44:45], v[60:61], v[86:87], v[44:45] neg_lo:[0,0,1] neg_hi:[0,0,1]
	s_nop 0
	v_pk_add_f32 v[134:135], v[44:45], v[42:43]
	v_pk_mul_f32 v[44:45], v[50:51], v[86:87]
	v_bfe_u32 v41, v134, 16, 1
	v_pk_fma_f32 v[44:45], v[60:61], v[46:47], v[44:45]
	v_add3_u32 v41, v134, v41, s29
	v_pk_add_f32 v[46:47], v[44:45], v[42:43] op_sel:[0,1] op_sel_hi:[1,0]
	ds_write_b16_d16_hi v88, v41 offset:5168
	v_bfe_u32 v41, v46, 16, 1
	v_add3_u32 v41, v46, v41, s29
	ds_write_b16_d16_hi v88, v41 offset:5296
	ds_read_b128 v[216:219], v248 offset:1280
	ds_read_b128 v[220:223], v248 offset:1296
	ds_read_b128 v[224:227], v248 offset:1312
	ds_read_b128 v[228:231], v248 offset:1328
	s_waitcnt lgkmcnt(0)
; #define LAS __attribute__((address_space(3)))
; __device__ __forceinline__ unsigned f2bf(float f) { unsigned u = __builtin_bit_cast(unsigned, f); return (u + 0x7fffu + ((u >> 16) & 1u)) >> 16; }
; __device__ __forceinline__ void s5_phase(LAS unsigned char* lds, const unsigned char* ws, const bf16_t* proj, const float* c_re, const float* c_im, const float* dskip, bf16_t* z,
;                                          int vcu, int G, int wave, int lane) {
;     ...
;             for (int k = 0; k < 32; ++k) {
;                 f32x2 xa = (f32x2){0.f, 0.f}, xb = (f32x2){0.f, 0.f};
; #pragma unroll
;                 for (int q = 0; q < 4; ++q) { const f32x4 u4 = *(const LAS f32x4*)(Uc + k * 16 + 4 * q);
;                     xa = __builtin_elementwise_fma((f32x2){u4[0], u4[0]}, (f32x2){bbre[4 * q], bbim[4 * q]}, xa);
;                     xb = __builtin_elementwise_fma((f32x2){u4[1], u4[1]}, (f32x2){bbre[4 * q + 1], bbim[4 * q + 1]}, xb);
;                     xa = __builtin_elementwise_fma((f32x2){u4[2], u4[2]}, (f32x2){bbre[4 * q + 2], bbim[4 * q + 2]}, xa);
;                     xb = __builtin_elementwise_fma((f32x2){u4[3], u4[3]}, (f32x2){bbre[4 * q + 3], bbim[4 * q + 3]}, xb); }
;                 const f32x2 xx = xa + xb;
;                 const float nr = are * hre - aim * him + xx[0], ni = are * him + aim * hre + xx[1]; hre = nr; him = ni;
;                 Hc[k * 136 + n] = (bf16_t)f2bf(hre); Hc[k * 136 + 64 + n] = (bf16_t)f2bf(him);
;             }
	v_mfma_f32_4x4x1_16b_f32 v[232:235], v216, v64, 0
	v_mfma_f32_4x4x1_16b_f32 v[236:239], v216, v65, 0
	v_mfma_f32_4x4x1_16b_f32 v[240:243], v217, v12, 0
	v_mfma_f32_4x4x1_16b_f32 v[244:247], v217, v13, 0
	v_mfma_f32_4x4x1_16b_f32 v[232:235], v218, v66, v[232:235]
	v_mfma_f32_4x4x1_16b_f32 v[236:239], v218, v67, v[236:239]
	v_mfma_f32_4x4x1_16b_f32 v[240:243], v219, v14, v[240:243]
	v_mfma_f32_4x4x1_16b_f32 v[244:247], v219, v15, v[244:247]
	v_mfma_f32_4x4x1_16b_f32 v[232:235], v220, v68, v[232:235]
	v_mfma_f32_4x4x1_16b_f32 v[236:239], v220, v69, v[236:239]
	v_mfma_f32_4x4x1_16b_f32 v[240:243], v221, v8, v[240:243]
	v_mfma_f32_4x4x1_16b_f32 v[244:247], v221, v9, v[244:247]
	v_mfma_f32_4x4x1_16b_f32 v[232:235], v222, v70, v[232:235]
	v_mfma_f32_4x4x1_16b_f32 v[236:239], v222, v71, v[236:239]
	v_mfma_f32_4x4x1_16b_f32 v[240:243], v223, v10, v[240:243]
	v_mfma_f32_4x4x1_16b_f32 v[244:247], v223, v11, v[244:247]
	v_mfma_f32_4x4x1_16b_f32 v[232:235], v224, v72, v[232:235]
	v_mfma_f32_4x4x1_16b_f32 v[236:239], v224, v73, v[236:239]
	v_mfma_f32_4x4x1_16b_f32 v[240:243], v225, v4, v[240:243]
	v_mfma_f32_4x4x1_16b_f32 v[244:247], v225, v5, v[244:247]
	v_mfma_f32_4x4x1_16b_f32 v[232:235], v226, v74, v[232:235]
	v_mfma_f32_4x4x1_16b_f32 v[236:239], v226, v75, v[236:239]
	v_mfma_f32_4x4x1_16b_f32 v[240:243], v227, v6, v[240:243]
	v_mfma_f32_4x4x1_16b_f32 v[244:247], v227, v7, v[244:247]
	v_mfma_f32_4x4x1_16b_f32 v[232:235], v228, v76, v[232:235]
	v_mfma_f32_4x4x1_16b_f32 v[236:239], v228, v77, v[236:239]
	v_mfma_f32_4x4x1_16b_f32 v[240:243], v229, v0, v[240:243]
	v_mfma_f32_4x4x1_16b_f32 v[244:247], v229, v1, v[244:247]
	v_mfma_f32_4x4x1_16b_f32 v[232:235], v230, v78, v[232:235]
	v_mfma_f32_4x4x1_16b_f32 v[236:239], v230, v79, v[236:239]
	v_mfma_f32_4x4x1_16b_f32 v[240:243], v231, v2, v[240:243]
	v_mfma_f32_4x4x1_16b_f32 v[244:247], v231, v3, v[244:247]
	s_nop 4
	v_add_f32_e32 v42, v240, v232
	v_add_f32_e32 v43, v244, v236
	v_pk_mul_f32 v[44:45], v[50:51], v[46:47]
	s_nop 0
	v_pk_fma_f32 v[44:45], v[60:61], v[134:135], v[44:45] neg_lo:[0,0,1] neg_hi:[0,0,1]
	s_nop 0
	v_pk_add_f32 v[86:87], v[44:45], v[42:43]
	v_pk_mul_f32 v[44:45], v[50:51], v[134:135]
	v_bfe_u32 v41, v86, 16, 1
	v_pk_fma_f32 v[44:45], v[60:61], v[46:47], v[44:45]
	v_add3_u32 v41, v86, v41, s29
	v_pk_add_f32 v[46:47], v[44:45], v[42:43] op_sel:[0,1] op_sel_hi:[1,0]
	ds_write_b16_d16_hi v88, v41 offset:5440
	v_bfe_u32 v41, v46, 16, 1
	v_add3_u32 v41, v46, v41, s29
	ds_write_b16_d16_hi v88, v41 offset:5568
	v_add_f32_e32 v42, v241, v233
	v_add_f32_e32 v43, v245, v237
	v_pk_mul_f32 v[44:45], v[50:51], v[46:47]
	s_nop 0
	v_pk_fma_f32 v[44:45], v[60:61], v[86:87], v[44:45] neg_lo:[0,0,1] neg_hi:[0,0,1]
	s_nop 0
	v_pk_add_f32 v[134:135], v[44:45], v[42:43]
	v_pk_mul_f32 v[44:45], v[50:51], v[86:87]
	v_bfe_u32 v41, v134, 16, 1
	v_pk_fma_f32 v[44:45], v[60:61], v[46:47], v[44:45]
	v_add3_u32 v41, v134, v41, s29
	v_pk_add_f32 v[46:47], v[44:45], v[42:43] op_sel:[0,1] op_sel_hi:[1,0]
	ds_write_b16_d16_hi v88, v41 offset:5712
	v_bfe_u32 v41, v46, 16, 1
	v_add3_u32 v41, v46, v41, s29
	ds_write_b16_d16_hi v88, v41 offset:5840
	v_add_f32_e32 v42, v242, v234
	v_add_f32_e32 v43, v246, v238
	v_pk_mul_f32 v[44:45], v[50:51], v[46:47]
	s_nop 0
	v_pk_fma_f32 v[44:45], v[60:61], v[134:135], v[44:45] neg_lo:[0,0,1] neg_hi:[0,0,1]
	s_nop 0
	v_pk_add_f32 v[86:87], v[44:45], v[42:43]
	v_pk_mul_f32 v[44:45], v[50:51], v[134:135]
	v_bfe_u32 v41, v86, 16, 1
	v_pk_fma_f32 v[44:45], v[60:61], v[46:47], v[44:45]
	v_add3_u32 v41, v86, v41, s29
	v_pk_add_f32 v[46:47], v[44:45], v[42:43] op_sel:[0,1] op_sel_hi:[1,0]
	ds_write_b16_d16_hi v88, v41 offset:5984
	v_bfe_u32 v41, v46, 16, 1
	v_add3_u32 v41, v46, v41, s29
	ds_write_b16_d16_hi v88, v41 offset:6112
	v_add_f32_e32 v42, v243, v235
	v_add_f32_e32 v43, v247, v239
	v_pk_mul_f32 v[44:45], v[50:51], v[46:47]
	s_nop 0
	v_pk_fma_f32 v[44:45], v[60:61], v[86:87], v[44:45] neg_lo:[0,0,1] neg_hi:[0,0,1]
	s_nop 0
	v_pk_add_f32 v[134:135], v[44:45], v[42:43]
	v_pk_mul_f32 v[44:45], v[50:51], v[86:87]
	v_bfe_u32 v41, v134, 16, 1
	v_pk_fma_f32 v[44:45], v[60:61], v[46:47], v[44:45]
	v_add3_u32 v41, v134, v41, s29
	v_pk_add_f32 v[46:47], v[44:45], v[42:43] op_sel:[0,1] op_sel_hi:[1,0]
	ds_write_b16_d16_hi v88, v41 offset:6256
	v_bfe_u32 v41, v46, 16, 1
	v_add3_u32 v41, v46, v41, s29
	ds_write_b16_d16_hi v88, v41 offset:6384
	ds_read_b128 v[216:219], v248 offset:1536
	ds_read_b128 v[220:223], v248 offset:1552
	ds_read_b128 v[224:227], v248 offset:1568
	ds_read_b128 v[228:231], v248 offset:1584
	s_waitcnt lgkmcnt(0)
; #define LAS __attribute__((address_space(3)))
; __device__ __forceinline__ unsigned f2bf(float f) { unsigned u = __builtin_bit_cast(unsigned, f); return (u + 0x7fffu + ((u >> 16) & 1u)) >> 16; }
; __device__ __forceinline__ void s5_phase(LAS unsigned char* lds, const unsigned char* ws, const bf16_t* proj, const float* c_re, const float* c_im, const float* dskip, bf16_t* z,
;                                          int vcu, int G, int wave, int lane) {
;     ...
;             for (int k = 0; k < 32; ++k) {
;                 f32x2 xa = (f32x2){0.f, 0.f}, xb = (f32x2){0.f, 0.f};
; #pragma unroll
;                 for (int q = 0; q < 4; ++q) { const f32x4 u4 = *(const LAS f32x4*)(Uc + k * 16 + 4 * q);
;                     xa = __builtin_elementwise_fma((f32x2){u4[0], u4[0]}, (f32x2){bbre[4 * q], bbim[4 * q]}, xa);
;                     xb = __builtin_elementwise_fma((f32x2){u4[1], u4[1]}, (f32x2){bbre[4 * q + 1], bbim[4 * q + 1]}, xb);
;                     xa = __builtin_elementwise_fma((f32x2){u4[2], u4[2]}, (f32x2){bbre[4 * q + 2], bbim[4 * q + 2]}, xa);
;                     xb = __builtin_elementwise_fma((f32x2){u4[3], u4[3]}, (f32x2){bbre[4 * q + 3], bbim[4 * q + 3]}, xb); }
;                 const f32x2 xx = xa + xb;
;                 const float nr = are * hre - aim * him + xx[0], ni = are * him + aim * hre + xx[1]; hre = nr; him = ni;
;                 Hc[k * 136 + n] = (bf16_t)f2bf(hre); Hc[k * 136 + 64 + n] = (bf16_t)f2bf(him);
	v_mfma_f32_4x4x1_16b_f32 v[232:235], v216, v64, 0
	v_mfma_f32_4x4x1_16b_f32 v[236:239], v216, v65, 0
	v_mfma_f32_4x4x1_16b_f32 v[240:243], v217, v12, 0
	v_mfma_f32_4x4x1_16b_f32 v[244:247], v217, v13, 0
	v_mfma_f32_4x4x1_16b_f32 v[232:235], v218, v66, v[232:235]
	v_mfma_f32_4x4x1_16b_f32 v[236:239], v218, v67, v[236:239]
	v_mfma_f32_4x4x1_16b_f32 v[240:243], v219, v14, v[240:243]
	v_mfma_f32_4x4x1_16b_f32 v[244:247], v219, v15, v[244:247]
	v_mfma_f32_4x4x1_16b_f32 v[232:235], v220, v68, v[232:235]
	v_mfma_f32_4x4x1_16b_f32 v[236:239], v220, v69, v[236:239]
	v_mfma_f32_4x4x1_16b_f32 v[240:243], v221, v8, v[240:243]
	v_mfma_f32_4x4x1_16b_f32 v[244:247], v221, v9, v[244:247]
	v_mfma_f32_4x4x1_16b_f32 v[232:235], v222, v70, v[232:235]
	v_mfma_f32_4x4x1_16b_f32 v[236:239], v222, v71, v[236:239]
	v_mfma_f32_4x4x1_16b_f32 v[240:243], v223, v10, v[240:243]
	v_mfma_f32_4x4x1_16b_f32 v[244:247], v223, v11, v[244:247]
	v_mfma_f32_4x4x1_16b_f32 v[232:235], v224, v72, v[232:235]
	v_mfma_f32_4x4x1_16b_f32 v[236:239], v224, v73, v[236:239]
	v_mfma_f32_4x4x1_16b_f32 v[240:243], v225, v4, v[240:243]
	v_mfma_f32_4x4x1_16b_f32 v[244:247], v225, v5, v[244:247]
	v_mfma_f32_4x4x1_16b_f32 v[232:235], v226, v74, v[232:235]
	v_mfma_f32_4x4x1_16b_f32 v[236:239], v226, v75, v[236:239]
	v_mfma_f32_4x4x1_16b_f32 v[240:243], v227, v6, v[240:243]
	v_mfma_f32_4x4x1_16b_f32 v[244:247], v227, v7, v[244:247]
	v_mfma_f32_4x4x1_16b_f32 v[232:235], v228, v76, v[232:235]
	v_mfma_f32_4x4x1_16b_f32 v[236:239], v228, v77, v[236:239]
	v_mfma_f32_4x4x1_16b_f32 v[240:243], v229, v0, v[240:243]
	v_mfma_f32_4x4x1_16b_f32 v[244:247], v229, v1, v[244:247]
	v_mfma_f32_4x4x1_16b_f32 v[232:235], v230, v78, v[232:235]
	v_mfma_f32_4x4x1_16b_f32 v[236:239], v230, v79, v[236:239]
	v_mfma_f32_4x4x1_16b_f32 v[240:243], v231, v2, v[240:243]
	v_mfma_f32_4x4x1_16b_f32 v[244:247], v231, v3, v[244:247]
	s_nop 4
	v_add_f32_e32 v42, v240, v232
	v_add_f32_e32 v43, v244, v236
	v_pk_mul_f32 v[44:45], v[50:51], v[46:47]
	s_nop 0
	v_pk_fma_f32 v[44:45], v[60:61], v[134:135], v[44:45] neg_lo:[0,0,1] neg_hi:[0,0,1]
	s_nop 0
	v_pk_add_f32 v[86:87], v[44:45], v[42:43]
	v_pk_mul_f32 v[44:45], v[50:51], v[134:135]
	v_bfe_u32 v41, v86, 16, 1
	v_pk_fma_f32 v[44:45], v[60:61], v[46:47], v[44:45]
	v_add3_u32 v41, v86, v41, s29
	v_pk_add_f32 v[46:47], v[44:45], v[42:43] op_sel:[0,1] op_sel_hi:[1,0]
	ds_write_b16_d16_hi v88, v41 offset:6528
	v_bfe_u32 v41, v46, 16, 1
	v_add3_u32 v41, v46, v41, s29
	ds_write_b16_d16_hi v88, v41 offset:6656
	v_add_f32_e32 v42, v241, v233
	v_add_f32_e32 v43, v245, v237
	v_pk_mul_f32 v[44:45], v[50:51], v[46:47]
	s_nop 0
	v_pk_fma_f32 v[44:45], v[60:61], v[86:87], v[44:45] neg_lo:[0,0,1] neg_hi:[0,0,1]
	s_nop 0
	v_pk_add_f32 v[134:135], v[44:45], v[42:43]
	v_pk_mul_f32 v[44:45], v[50:51], v[86:87]
	v_bfe_u32 v41, v134, 16, 1
	v_pk_fma_f32 v[44:45], v[60:61], v[46:47], v[44:45]
	v_add3_u32 v41, v134, v41, s29
	v_pk_add_f32 v[46:47], v[44:45], v[42:43] op_sel:[0,1] op_sel_hi:[1,0]
	ds_write_b16_d16_hi v88, v41 offset:6800
	v_bfe_u32 v41, v46, 16, 1
	v_add3_u32 v41, v46, v41, s29
	ds_write_b16_d16_hi v88, v41 offset:6928
	v_add_f32_e32 v42, v242, v234
	v_add_f32_e32 v43, v246, v238
	v_pk_mul_f32 v[44:45], v[50:51], v[46:47]
	s_nop 0
	v_pk_fma_f32 v[44:45], v[60:61], v[134:135], v[44:45] neg_lo:[0,0,1] neg_hi:[0,0,1]
	s_nop 0
	v_pk_add_f32 v[86:87], v[44:45], v[42:43]
	v_pk_mul_f32 v[44:45], v[50:51], v[134:135]
	v_bfe_u32 v41, v86, 16, 1
	v_pk_fma_f32 v[44:45], v[60:61], v[46:47], v[44:45]
	v_add3_u32 v41, v86, v41, s29
	v_pk_add_f32 v[46:47], v[44:45], v[42:43] op_sel:[0,1] op_sel_hi:[1,0]
	ds_write_b16_d16_hi v88, v41 offset:7072
	v_bfe_u32 v41, v46, 16, 1
	v_add3_u32 v41, v46, v41, s29
	ds_write_b16_d16_hi v88, v41 offset:7200
	v_add_f32_e32 v42, v243, v235
	v_add_f32_e32 v43, v247, v239
	v_pk_mul_f32 v[44:45], v[50:51], v[46:47]
	s_nop 0
	v_pk_fma_f32 v[44:45], v[60:61], v[86:87], v[44:45] neg_lo:[0,0,1] neg_hi:[0,0,1]
	s_nop 0
	v_pk_add_f32 v[134:135], v[44:45], v[42:43]
	v_pk_mul_f32 v[44:45], v[50:51], v[86:87]
	v_bfe_u32 v41, v134, 16, 1
	v_pk_fma_f32 v[44:45], v[60:61], v[46:47], v[44:45]
	v_add3_u32 v41, v134, v41, s29
	v_pk_add_f32 v[46:47], v[44:45], v[42:43] op_sel:[0,1] op_sel_hi:[1,0]
	ds_write_b16_d16_hi v88, v41 offset:7344
	v_bfe_u32 v41, v46, 16, 1
	v_add3_u32 v41, v46, v41, s29
	ds_write_b16_d16_hi v88, v41 offset:7472
	ds_read_b128 v[216:219], v248 offset:1792
	ds_read_b128 v[220:223], v248 offset:1808
	ds_read_b128 v[224:227], v248 offset:1824
	ds_read_b128 v[228:231], v248 offset:1840
	s_waitcnt lgkmcnt(0)
; #define LAS __attribute__((address_space(3)))
; __device__ __forceinline__ unsigned f2bf(float f) { unsigned u = __builtin_bit_cast(unsigned, f); return (u + 0x7fffu + ((u >> 16) & 1u)) >> 16; }
; __device__ __forceinline__ void s5_phase(LAS unsigned char* lds, const unsigned char* ws, const bf16_t* proj, const float* c_re, const float* c_im, const float* dskip, bf16_t* z,
;                                          int vcu, int G, int wave, int lane) {
;     ...
;             for (int k = 0; k < 32; ++k) {
;                 f32x2 xa = (f32x2){0.f, 0.f}, xb = (f32x2){0.f, 0.f};
; #pragma unroll
;                 for (int q = 0; q < 4; ++q) { const f32x4 u4 = *(const LAS f32x4*)(Uc + k * 16 + 4 * q);
;                     xa = __builtin_elementwise_fma((f32x2){u4[0], u4[0]}, (f32x2){bbre[4 * q], bbim[4 * q]}, xa);
;                     xb = __builtin_elementwise_fma((f32x2){u4[1], u4[1]}, (f32x2){bbre[4 * q + 1], bbim[4 * q + 1]}, xb);
;                     xa = __builtin_elementwise_fma((f32x2){u4[2], u4[2]}, (f32x2){bbre[4 * q + 2], bbim[4 * q + 2]}, xa);
;                     xb = __builtin_elementwise_fma((f32x2){u4[3], u4[3]}, (f32x2){bbre[4 * q + 3], bbim[4 * q + 3]}, xb); }
;                 const f32x2 xx = xa + xb;
;                 const float nr = are * hre - aim * him + xx[0], ni = are * him + aim * hre + xx[1]; hre = nr; him = ni;
;                 Hc[k * 136 + n] = (bf16_t)f2bf(hre); Hc[k * 136 + 64 + n] = (bf16_t)f2bf(him);
;             }
; #pragma unroll
;             for (int sb = 0; sb < 2; ++sb) {
;                 f32x4 y = (f32x4){0.f, 0.f, 0.f, 0.f};
; #pragma unroll
;                 for (int ks = 0; ks < 4; ++ks) { const bf16x8 hf = *(const LAS bf16x8*)(Hc + (16 * sb + fr) * 136 + 32 * ks + 8 * fq); y = __builtin_amdgcn_mfma_f32_16x16x32_bf16(hf, cf[ks], y, 0, 0, 0); }
	v_mfma_f32_4x4x1_16b_f32 v[232:235], v216, v64, 0
	v_mfma_f32_4x4x1_16b_f32 v[236:239], v216, v65, 0
	v_mfma_f32_4x4x1_16b_f32 v[240:243], v217, v12, 0
	v_mfma_f32_4x4x1_16b_f32 v[244:247], v217, v13, 0
	v_mfma_f32_4x4x1_16b_f32 v[232:235], v218, v66, v[232:235]
	v_mfma_f32_4x4x1_16b_f32 v[236:239], v218, v67, v[236:239]
	v_mfma_f32_4x4x1_16b_f32 v[240:243], v219, v14, v[240:243]
	v_mfma_f32_4x4x1_16b_f32 v[244:247], v219, v15, v[244:247]
	v_mfma_f32_4x4x1_16b_f32 v[232:235], v220, v68, v[232:235]
	v_mfma_f32_4x4x1_16b_f32 v[236:239], v220, v69, v[236:239]
	v_mfma_f32_4x4x1_16b_f32 v[240:243], v221, v8, v[240:243]
	v_mfma_f32_4x4x1_16b_f32 v[244:247], v221, v9, v[244:247]
	v_mfma_f32_4x4x1_16b_f32 v[232:235], v222, v70, v[232:235]
	v_mfma_f32_4x4x1_16b_f32 v[236:239], v222, v71, v[236:239]
	v_mfma_f32_4x4x1_16b_f32 v[240:243], v223, v10, v[240:243]
	v_mfma_f32_4x4x1_16b_f32 v[244:247], v223, v11, v[244:247]
	v_mfma_f32_4x4x1_16b_f32 v[232:235], v224, v72, v[232:235]
	v_mfma_f32_4x4x1_16b_f32 v[236:239], v224, v73, v[236:239]
	v_mfma_f32_4x4x1_16b_f32 v[240:243], v225, v4, v[240:243]
	v_mfma_f32_4x4x1_16b_f32 v[244:247], v225, v5, v[244:247]
	v_mfma_f32_4x4x1_16b_f32 v[232:235], v226, v74, v[232:235]
	v_mfma_f32_4x4x1_16b_f32 v[236:239], v226, v75, v[236:239]
	v_mfma_f32_4x4x1_16b_f32 v[240:243], v227, v6, v[240:243]
	v_mfma_f32_4x4x1_16b_f32 v[244:247], v227, v7, v[244:247]
	v_mfma_f32_4x4x1_16b_f32 v[232:235], v228, v76, v[232:235]
	v_mfma_f32_4x4x1_16b_f32 v[236:239], v228, v77, v[236:239]
	v_mfma_f32_4x4x1_16b_f32 v[240:243], v229, v0, v[240:243]
	v_mfma_f32_4x4x1_16b_f32 v[244:247], v229, v1, v[244:247]
	v_mfma_f32_4x4x1_16b_f32 v[232:235], v230, v78, v[232:235]
	v_mfma_f32_4x4x1_16b_f32 v[236:239], v230, v79, v[236:239]
	v_mfma_f32_4x4x1_16b_f32 v[240:243], v231, v2, v[240:243]
	v_mfma_f32_4x4x1_16b_f32 v[244:247], v231, v3, v[244:247]
	s_nop 4
	v_add_f32_e32 v42, v240, v232
	v_add_f32_e32 v43, v244, v236
	v_pk_mul_f32 v[44:45], v[50:51], v[46:47]
	s_nop 0
	v_pk_fma_f32 v[44:45], v[60:61], v[134:135], v[44:45] neg_lo:[0,0,1] neg_hi:[0,0,1]
	s_nop 0
	v_pk_add_f32 v[86:87], v[44:45], v[42:43]
	v_pk_mul_f32 v[44:45], v[50:51], v[134:135]
	v_bfe_u32 v41, v86, 16, 1
	v_pk_fma_f32 v[44:45], v[60:61], v[46:47], v[44:45]
	v_add3_u32 v41, v86, v41, s29
	v_pk_add_f32 v[46:47], v[44:45], v[42:43] op_sel:[0,1] op_sel_hi:[1,0]
	ds_write_b16_d16_hi v88, v41 offset:7616
	v_bfe_u32 v41, v46, 16, 1
	v_add3_u32 v41, v46, v41, s29
	ds_write_b16_d16_hi v88, v41 offset:7744
	v_add_f32_e32 v42, v241, v233
	v_add_f32_e32 v43, v245, v237
	v_pk_mul_f32 v[44:45], v[50:51], v[46:47]
	s_nop 0
	v_pk_fma_f32 v[44:45], v[60:61], v[86:87], v[44:45] neg_lo:[0,0,1] neg_hi:[0,0,1]
	s_nop 0
	v_pk_add_f32 v[134:135], v[44:45], v[42:43]
	v_pk_mul_f32 v[44:45], v[50:51], v[86:87]
	v_bfe_u32 v41, v134, 16, 1
	v_pk_fma_f32 v[44:45], v[60:61], v[46:47], v[44:45]
	v_add3_u32 v41, v134, v41, s29
	v_pk_add_f32 v[46:47], v[44:45], v[42:43] op_sel:[0,1] op_sel_hi:[1,0]
	ds_write_b16_d16_hi v88, v41 offset:7888
	v_bfe_u32 v41, v46, 16, 1
	v_add3_u32 v41, v46, v41, s29
	ds_write_b16_d16_hi v88, v41 offset:8016
	v_add_f32_e32 v42, v242, v234
	v_add_f32_e32 v43, v246, v238
	v_pk_mul_f32 v[44:45], v[50:51], v[46:47]
	s_nop 0
	v_pk_fma_f32 v[44:45], v[60:61], v[134:135], v[44:45] neg_lo:[0,0,1] neg_hi:[0,0,1]
	s_nop 0
	v_pk_add_f32 v[86:87], v[44:45], v[42:43]
	v_pk_mul_f32 v[44:45], v[50:51], v[134:135]
	v_bfe_u32 v41, v86, 16, 1
	v_pk_fma_f32 v[44:45], v[60:61], v[46:47], v[44:45]
	v_add3_u32 v41, v86, v41, s29
	v_pk_add_f32 v[46:47], v[44:45], v[42:43] op_sel:[0,1] op_sel_hi:[1,0]
	ds_write_b16_d16_hi v88, v41 offset:8160
	v_bfe_u32 v41, v46, 16, 1
	v_add3_u32 v41, v46, v41, s29
	ds_write_b16_d16_hi v88, v41 offset:8288
	v_add_f32_e32 v40, v243, v235
	v_add_f32_e32 v41, v247, v239
	v_pk_mul_f32 v[42:43], v[80:81], v[46:47] op_sel_hi:[1,0]
	v_lshl_add_u64 v[130:131], v[82:83], 0, s[26:27]
	v_pk_fma_f32 v[44:45], v[60:61], v[86:87], v[42:43] neg_lo:[0,0,1] neg_hi:[0,0,1]
	v_pk_fma_f32 v[42:43], v[60:61], v[86:87], v[42:43] op_sel_hi:[1,0,1]
	s_nop 0
	v_mov_b32_e32 v45, v43
	v_pk_add_f32 v[86:87], v[44:45], v[40:41]
	s_nop 0
	v_bfe_u32 v40, v86, 16, 1
	v_add3_u32 v40, v86, v40, s29
	ds_write_b16_d16_hi v88, v40 offset:8432
	v_bfe_u32 v40, v87, 16, 1
	v_add3_u32 v40, v87, v40, s29
	ds_write_b16_d16_hi v88, v40 offset:8560
	ds_read_b128 v[40:43], v102
	ds_read_b128 v[44:47], v102 offset:64
	s_waitcnt lgkmcnt(1)
	v_mfma_f32_16x16x32_bf16 v[40:43], v[40:43], v[16:19], 0
	ds_read_b128 v[122:125], v102 offset:128
	ds_read_b128 v[126:129], v102 offset:4544
	s_waitcnt lgkmcnt(2)
	v_mfma_f32_16x16x32_bf16 v[40:43], v[44:47], v[20:23], v[40:43]
	ds_read_b128 v[44:47], v102 offset:192
	s_waitcnt lgkmcnt(2)
	v_mfma_f32_16x16x32_bf16 v[40:43], v[122:125], v[24:27], v[40:43]
	ds_read_b128 v[122:125], v102 offset:4480
	s_waitcnt lgkmcnt(1)
; #define LAS __attribute__((address_space(3)))
; __device__ __forceinline__ unsigned f2bf(float f) { unsigned u = __builtin_bit_cast(unsigned, f); return (u + 0x7fffu + ((u >> 16) & 1u)) >> 16; }
; __device__ __forceinline__ float gelu_tanh_f(float y) { return y * fast_sigmoid(1.5957691216057308f * (y + 0.044715f * y * y * y)); }
; __device__ __forceinline__ void s5_phase(LAS unsigned char* lds, const unsigned char* ws, const bf16_t* proj, const float* c_re, const float* c_im, const float* dskip, bf16_t* z,
;                                          int vcu, int G, int wave, int lane) {
;     ...
; #pragma unroll
;             for (int sb = 0; sb < 2; ++sb) {
;                 f32x4 y = (f32x4){0.f, 0.f, 0.f, 0.f};
; #pragma unroll
;                 for (int ks = 0; ks < 4; ++ks) { const bf16x8 hf = *(const LAS bf16x8*)(Hc + (16 * sb + fr) * 136 + 32 * ks + 8 * fq); y = __builtin_amdgcn_mfma_f32_16x16x32_bf16(hf, cf[ks], y, 0, 0, 0); }
; #pragma unroll
;                 for (int i = 0; i < 4; ++i) { const size_t row = row0 + 16 * sb + 4 * fq + i;
;                     const float yy = y[i] + dsk * bf2f(uu[sb][i]);
;                     z[row * 1024 + g * 16 + fr] = (bf16_t)f2bf(gelu_tanh_f(yy)); }
;             }
;             ua = ua_n; ub = ub_n;
; #pragma unroll
;             for (int sb = 0; sb < 2; ++sb)
; #pragma unroll
;                 for (int i = 0; i < 4; ++i) uu[sb][i] = uu_n[sb][i];
	v_mfma_f32_16x16x32_bf16 v[40:43], v[44:47], v[28:31], v[40:43]
	v_lshlrev_b32_e32 v44, 16, v120
	s_nop 6
	v_fma_f32 v40, v104, v44, v40
	v_mul_f32_e32 v44, 0x3d372713, v40
	v_mul_f32_e32 v44, v40, v44
	v_fma_f32 v44, v40, v44, v40
	v_mul_f32_e32 v44, 0x3fcc422a, v44
	v_mul_f32_e32 v44, 0xbfb8aa3b, v44
	v_exp_f32_e32 v44, v44
	s_nop 0
	v_add_f32_e32 v44, 1.0, v44
	v_rcp_f32_e32 v44, v44
	s_nop 0
	v_mul_f32_e32 v40, v40, v44
	v_bfe_u32 v44, v40, 16, 1
	v_add3_u32 v46, v40, v44, s29
	v_lshlrev_b32_e32 v40, 16, v119
	v_fma_f32 v47, v104, v40, v41
	v_mul_f32_e32 v40, 0x3d372713, v47
	v_mul_f32_e32 v40, v47, v40
	v_fma_f32 v40, v47, v40, v47
	v_mul_f32_e32 v40, 0x3fcc422a, v40
	v_mul_f32_e32 v40, 0xbfb8aa3b, v40
	v_lshl_add_u64 v[44:45], v[84:85], 0, s[26:27]
	v_exp_f32_e32 v119, v40
	v_add_co_u32_e64 v40, s[0:1], s31, v44
	s_add_u32 s26, s26, 0x10000
	s_nop 0
	v_addc_co_u32_e64 v41, s[0:1], 0, v45, s[0:1]
	v_add_co_u32_e64 v132, s[0:1], s33, v44
	v_add_f32_e32 v119, 1.0, v119
	s_nop 0
	v_addc_co_u32_e64 v133, s[0:1], 0, v45, s[0:1]
	v_rcp_f32_e32 v119, v119
	global_store_short_d16_hi v[132:133], v46, off offset:-4096
	v_lshlrev_b32_e32 v46, 16, v118
	v_fma_f32 v42, v104, v46, v42
	v_mul_f32_e32 v46, 0x3d372713, v42
	v_mul_f32_e32 v46, v42, v46
	v_mul_f32_e32 v44, v47, v119
	v_fma_f32 v46, v42, v46, v42
	v_bfe_u32 v45, v44, 16, 1
	v_mul_f32_e32 v46, 0x3fcc422a, v46
	v_mul_f32_e32 v46, 0xbfb8aa3b, v46
	v_add3_u32 v44, v44, v45, s29
	v_exp_f32_e32 v118, v46
	global_store_short_d16_hi v[40:41], v44, off offset:2048
	ds_read_b128 v[44:47], v102 offset:4352
	v_lshlrev_b32_e32 v41, 16, v109
	v_add_f32_e32 v40, 1.0, v118
	ds_read_b128 v[118:121], v102 offset:4416
	s_waitcnt lgkmcnt(1)
	v_mfma_f32_16x16x32_bf16 v[44:47], v[44:47], v[16:19], 0
	v_fmac_f32_e32 v43, v104, v41
	v_mul_f32_e32 v41, 0x3d372713, v43
	v_mul_f32_e32 v41, v43, v41
	s_waitcnt lgkmcnt(0)
	v_mfma_f32_16x16x32_bf16 v[44:47], v[118:121], v[20:23], v[44:47]
	v_fma_f32 v41, v43, v41, v43
	v_mul_f32_e32 v41, 0x3fcc422a, v41
	v_mul_f32_e32 v41, 0xbfb8aa3b, v41
	v_mfma_f32_16x16x32_bf16 v[44:47], v[122:125], v[24:27], v[44:47]
	v_exp_f32_e32 v41, v41
	v_rcp_f32_e32 v40, v40
	s_addc_u32 s27, s27, 0
	v_mfma_f32_16x16x32_bf16 v[44:47], v[126:129], v[28:31], v[44:47]
	v_add_f32_e32 v41, 1.0, v41
	v_rcp_f32_e32 v41, v41
	v_mul_f32_e32 v40, v42, v40
	v_bfe_u32 v42, v40, 16, 1
	v_add3_u32 v40, v40, v42, s29
	s_nop 2
	v_fma_f32 v44, v104, v108, v44
	v_mul_f32_e32 v108, 0x3d372713, v44
	v_mul_f32_e32 v108, v44, v108
	v_fma_f32 v108, v44, v108, v44
	v_mul_f32_e32 v108, 0x3fcc422a, v108
	v_mul_f32_e32 v108, 0xbfb8aa3b, v108
	v_exp_f32_e32 v108, v108
	global_store_short_d16_hi v[132:133], v40, off
	v_mul_f32_e32 v40, v43, v41
	v_bfe_u32 v42, v40, 16, 1
	v_add_f32_e32 v41, 1.0, v108
	v_rcp_f32_e32 v41, v41
	v_add3_u32 v40, v40, v42, s29
	global_store_short_d16_hi v[132:133], v40, off offset:2048
	s_add_i32 s34, s34, 0x28000
	v_mul_f32_e32 v40, v44, v41
	s_waitcnt vmcnt(16)
	v_lshlrev_b32_e32 v41, 16, v107
	v_fma_f32 v42, v104, v41, v45
	v_mul_f32_e32 v41, 0x3d372713, v42
	v_mul_f32_e32 v41, v42, v41
	v_fma_f32 v41, v42, v41, v42
	v_mul_f32_e32 v41, 0x3fcc422a, v41
	v_mul_f32_e32 v41, 0xbfb8aa3b, v41
	v_exp_f32_e32 v41, v41
	v_bfe_u32 v43, v40, 16, 1
	v_add3_u32 v43, v40, v43, s29
	v_or_b32_e32 v40, 0x8000, v130
	v_add_f32_e32 v41, 1.0, v41
	v_rcp_f32_e32 v44, v41
	v_mov_b32_e32 v41, v131
	v_lshl_add_u64 v[40:41], v[62:63], 0, v[40:41]
	global_store_short_d16_hi v[40:41], v43, off
	s_waitcnt vmcnt(16)
	v_lshlrev_b32_e32 v41, 16, v106
	v_mul_f32_e32 v40, v42, v44
	v_fma_f32 v42, v104, v41, v46
	v_mul_f32_e32 v41, 0x3d372713, v42
	v_mul_f32_e32 v41, v42, v41
	v_fma_f32 v41, v42, v41, v42
	v_mul_f32_e32 v41, 0x3fcc422a, v41
	v_mul_f32_e32 v41, 0xbfb8aa3b, v41
	v_exp_f32_e32 v41, v41
	v_bfe_u32 v43, v40, 16, 1
	v_add3_u32 v43, v40, v43, s29
	v_or_b32_e32 v40, 0x8800, v130
	v_add_f32_e32 v41, 1.0, v41
	v_rcp_f32_e32 v44, v41
	v_mov_b32_e32 v41, v131
	v_lshl_add_u64 v[40:41], v[62:63], 0, v[40:41]
	global_store_short_d16_hi v[40:41], v43, off
	s_waitcnt vmcnt(16)
	v_lshlrev_b32_e32 v41, 16, v105
	v_fmac_f32_e32 v47, v104, v41
	v_mul_f32_e32 v41, 0x3d372713, v47
	v_mul_f32_e32 v41, v47, v41
	v_fma_f32 v41, v47, v41, v47
	v_mul_f32_e32 v41, 0x3fcc422a, v41
	v_mul_f32_e32 v41, 0xbfb8aa3b, v41
	v_exp_f32_e32 v41, v41
	v_mul_f32_e32 v40, v42, v44
	v_bfe_u32 v42, v40, 16, 1
	v_add3_u32 v42, v40, v42, s29
	v_add_f32_e32 v41, 1.0, v41
	v_rcp_f32_e32 v43, v41
	v_or_b32_e32 v40, 0x9000, v130
	v_mov_b32_e32 v41, v131
	v_lshl_add_u64 v[40:41], v[62:63], 0, v[40:41]
	global_store_short_d16_hi v[40:41], v42, off
	v_mul_f32_e32 v40, v47, v43
	v_bfe_u32 v41, v40, 16, 1
	v_or_b32_e32 v130, 0x9800, v130
	v_add3_u32 v42, v40, v41, s29
	v_lshl_add_u64 v[40:41], v[62:63], 0, v[130:131]
	global_store_short_d16_hi v[40:41], v42, off
	s_waitcnt vmcnt(16)
	v_mov_b64_e32 v[46:47], v[38:39]
	v_mov_b64_e32 v[42:43], v[34:35]
	s_cmp_eq_u32 s26, 0x400000
	s_waitcnt vmcnt(13)
	v_mov_b32_e32 v118, v117
	v_mov_b32_e32 v119, v111
	v_mov_b32_e32 v120, v110
	s_waitcnt vmcnt(12)
	v_mov_b32_e32 v109, v112
	s_waitcnt vmcnt(11)
	v_mov_b32_e32 v108, v113
	s_waitcnt vmcnt(10)
	v_mov_b32_e32 v107, v114
	s_waitcnt vmcnt(9)
	v_mov_b32_e32 v106, v115
	s_waitcnt vmcnt(8)
	v_mov_b32_e32 v105, v116
	v_mov_b64_e32 v[44:45], v[36:37]
	v_mov_b64_e32 v[40:41], v[32:33]
	s_cbranch_scc1 .LBB0_384
